# FFN-up K-loop: first-iteration vmcnt waits of each non-first unit raised by the 16 younger epilogue stores/row-stat loads (in-order counter); phase-0 gain-load change dropped
# baseline (speedup 1.0000x reference)
.LBB0_561:
	s_add_u32 s2, s40, 0xfffc0080
	s_addc_u32 s3, s41, -1
	s_add_i32 s47, 0, 0x10000
	s_cmp_eq_u32 s46, 12
	s_cselect_b32 s7, s37, s3
	s_cselect_b32 s6, s58, s2
	v_add_u32_e32 v160, s47, v147
	s_cselect_b32 s3, s35, s61
	s_cselect_b32 s2, s59, s60
	s_add_i32 s64, 0, 0x14000
	ds_read_b128 v[164:167], v160
	ds_read_b128 v[184:187], v160 offset:1024
	ds_read_b128 v[188:191], v160 offset:2048
	ds_read_b128 v[192:195], v160 offset:3072
	v_add_u32_e32 v160, s64, v147
	ds_read_b128 v[196:199], v160
	ds_read_b128 v[200:203], v160 offset:1024
	ds_read_b128 v[204:207], v160 offset:2048
	ds_read_b128 v[208:211], v160 offset:3072
	v_lshl_add_u64 v[160:161], s[40:41], 0, v[138:139]
	s_add_i32 m0, s21, 0xc000
	ds_read_b128 v[212:215], v163
	ds_read_b128 v[216:219], v163 offset:1024
	ds_read_b128 v[224:227], v163 offset:2048
	ds_read_b128 v[228:231], v163 offset:3072
	ds_read_b128 v[232:235], v163 offset:4096
	ds_read_b128 v[236:239], v163 offset:5120
	ds_read_b128 v[240:243], v163 offset:6144
	ds_read_b128 v[244:247], v163 offset:7168
	global_load_lds_dwordx4 v[160:161], off
	v_lshl_add_u64 v[160:161], s[40:41], 0, v[136:137]
	s_add_i32 m0, s21, 0xe000
	s_nop 0
	global_load_lds_dwordx4 v[160:161], off
	s_cmp_lg_u32 s46, 0xfffffffe
	s_cbranch_scc1 .Lw8_i3_1
	s_cmp_eq_u32 s56, 1
	s_cbranch_scc1 .Lw8_i3_1
	s_waitcnt vmcnt(24)
	s_branch .Lwd_i3_1
.Lw8_i3_1:
	s_waitcnt vmcnt(8)
.Lwd_i3_1:
	s_waitcnt lgkmcnt(0)
	s_barrier
	s_setprio 1
	s_waitcnt lgkmcnt(0)
	v_mfma_f32_16x16x32_bf16 v[126:129], v[164:167], v[212:215], v[126:129]
	v_mfma_f32_16x16x32_bf16 v[122:125], v[188:191], v[212:215], v[122:125]
	v_mfma_f32_16x16x32_bf16 v[110:113], v[164:167], v[224:227], v[110:113]
	v_mfma_f32_16x16x32_bf16 v[106:109], v[188:191], v[224:227], v[106:109]
	v_mfma_f32_16x16x32_bf16 v[94:97], v[164:167], v[232:235], v[94:97]
	v_mfma_f32_16x16x32_bf16 v[90:93], v[188:191], v[232:235], v[90:93]
	v_mfma_f32_16x16x32_bf16 v[78:81], v[164:167], v[240:243], v[78:81]
	v_mfma_f32_16x16x32_bf16 v[74:77], v[188:191], v[240:243], v[74:77]
	v_mfma_f32_16x16x32_bf16 v[126:129], v[184:187], v[216:219], v[126:129]
	v_mfma_f32_16x16x32_bf16 v[122:125], v[192:195], v[216:219], v[122:125]
	v_mfma_f32_16x16x32_bf16 v[110:113], v[184:187], v[228:231], v[110:113]
	v_mfma_f32_16x16x32_bf16 v[106:109], v[192:195], v[228:231], v[106:109]
	v_mfma_f32_16x16x32_bf16 v[94:97], v[184:187], v[236:239], v[94:97]
	v_mfma_f32_16x16x32_bf16 v[90:93], v[192:195], v[236:239], v[90:93]
	v_mfma_f32_16x16x32_bf16 v[78:81], v[184:187], v[244:247], v[78:81]
	v_mfma_f32_16x16x32_bf16 v[74:77], v[192:195], v[244:247], v[74:77]
	s_setprio 0
	s_setprio 1
	v_mfma_f32_16x16x32_bf16 v[118:121], v[196:199], v[212:215], v[118:121]
	v_mfma_f32_16x16x32_bf16 v[114:117], v[204:207], v[212:215], v[114:117]
	v_mfma_f32_16x16x32_bf16 v[102:105], v[196:199], v[224:227], v[102:105]
	v_mfma_f32_16x16x32_bf16 v[98:101], v[204:207], v[224:227], v[98:101]
	v_mfma_f32_16x16x32_bf16 v[86:89], v[196:199], v[232:235], v[86:89]
	v_mfma_f32_16x16x32_bf16 v[82:85], v[204:207], v[232:235], v[82:85]
	v_mfma_f32_16x16x32_bf16 v[70:73], v[196:199], v[240:243], v[70:73]
	v_mfma_f32_16x16x32_bf16 v[66:69], v[204:207], v[240:243], v[66:69]
	v_mfma_f32_16x16x32_bf16 v[118:121], v[200:203], v[216:219], v[118:121]
	v_mfma_f32_16x16x32_bf16 v[114:117], v[208:211], v[216:219], v[114:117]
	v_mfma_f32_16x16x32_bf16 v[102:105], v[200:203], v[228:231], v[102:105]
	v_mfma_f32_16x16x32_bf16 v[98:101], v[208:211], v[228:231], v[98:101]
	v_mfma_f32_16x16x32_bf16 v[86:89], v[200:203], v[236:239], v[86:89]
	v_mfma_f32_16x16x32_bf16 v[82:85], v[208:211], v[236:239], v[82:85]
	v_mfma_f32_16x16x32_bf16 v[70:73], v[200:203], v[244:247], v[70:73]
	v_mfma_f32_16x16x32_bf16 v[66:69], v[208:211], v[244:247], v[66:69]
	s_setprio 0
	s_barrier
	s_add_i32 s47, s47, s48
	v_lshl_add_u64 v[160:161], s[2:3], 0, v[0:1]
	s_mov_b32 m0, s47
	ds_read_b128 v[212:215], v163 offset:16384
	ds_read_b128 v[216:219], v163 offset:17408
	ds_read_b128 v[224:227], v163 offset:18432
	ds_read_b128 v[228:231], v163 offset:19456
	ds_read_b128 v[232:235], v163 offset:20480
	ds_read_b128 v[236:239], v163 offset:21504
	ds_read_b128 v[240:243], v163 offset:22528
	ds_read_b128 v[244:247], v163 offset:23552
	global_load_lds_dwordx4 v[160:161], off
	s_add_i32 m0, s47, 0x2000
	s_add_u32 s62, s2, 0x40000
	v_lshl_add_u64 v[168:169], s[2:3], 0, v[130:131]
	s_addc_u32 s63, s3, 0
	s_add_i32 s47, s64, s48
	global_load_lds_dwordx4 v[168:169], off
	v_lshl_add_u64 v[248:249], s[62:63], 0, v[0:1]
	s_mov_b32 m0, s47
	v_lshl_add_u64 v[250:251], s[6:7], 0, v[132:133]
	global_load_lds_dwordx4 v[248:249], off
	v_lshl_add_u64 v[248:249], s[62:63], 0, v[130:131]
	s_add_i32 m0, s47, 0x2000
	s_nop 0
	global_load_lds_dwordx4 v[248:249], off
	v_lshl_add_u64 v[248:249], s[6:7], 0, v[134:135]
	s_mov_b32 m0, s21
	s_nop 0
	global_load_lds_dwordx4 v[248:249], off
	s_mov_b32 m0, s50
	s_nop 0
	global_load_lds_dwordx4 v[250:251], off
	s_cmp_lg_u32 s46, 0xfffffffe
	s_cbranch_scc1 .Lw8_i3_0
	s_cmp_eq_u32 s56, 1
	s_cbranch_scc1 .Lw8_i3_0
	s_waitcnt vmcnt(24)
	s_branch .Lwd_i3_0

.Lwd_i3_0:
	s_waitcnt lgkmcnt(0)
	s_barrier
	s_setprio 1
	s_waitcnt lgkmcnt(0)
	v_mfma_f32_16x16x32_bf16 v[62:65], v[164:167], v[212:215], v[62:65]
	v_mfma_f32_16x16x32_bf16 v[58:61], v[188:191], v[212:215], v[58:61]
	v_mfma_f32_16x16x32_bf16 v[46:49], v[164:167], v[224:227], v[46:49]
	v_mfma_f32_16x16x32_bf16 v[42:45], v[188:191], v[224:227], v[42:45]
	v_mfma_f32_16x16x32_bf16 v[30:33], v[164:167], v[232:235], v[30:33]
	v_mfma_f32_16x16x32_bf16 v[26:29], v[188:191], v[232:235], v[26:29]
	v_mfma_f32_16x16x32_bf16 v[14:17], v[164:167], v[240:243], v[14:17]
	v_mfma_f32_16x16x32_bf16 v[10:13], v[188:191], v[240:243], v[10:13]
	v_mfma_f32_16x16x32_bf16 v[62:65], v[184:187], v[216:219], v[62:65]
	v_mfma_f32_16x16x32_bf16 v[58:61], v[192:195], v[216:219], v[58:61]
	v_mfma_f32_16x16x32_bf16 v[46:49], v[184:187], v[228:231], v[46:49]
	v_mfma_f32_16x16x32_bf16 v[42:45], v[192:195], v[228:231], v[42:45]
	v_mfma_f32_16x16x32_bf16 v[30:33], v[184:187], v[236:239], v[30:33]
	v_mfma_f32_16x16x32_bf16 v[26:29], v[192:195], v[236:239], v[26:29]
	v_mfma_f32_16x16x32_bf16 v[14:17], v[184:187], v[244:247], v[14:17]
	v_mfma_f32_16x16x32_bf16 v[10:13], v[192:195], v[244:247], v[10:13]
	s_setprio 0
	s_setprio 1
	v_mfma_f32_16x16x32_bf16 v[54:57], v[196:199], v[212:215], v[54:57]
	v_mfma_f32_16x16x32_bf16 v[50:53], v[204:207], v[212:215], v[50:53]
	v_mfma_f32_16x16x32_bf16 v[38:41], v[196:199], v[224:227], v[38:41]
	v_mfma_f32_16x16x32_bf16 v[34:37], v[204:207], v[224:227], v[34:37]
	v_mfma_f32_16x16x32_bf16 v[22:25], v[196:199], v[232:235], v[22:25]
	v_mfma_f32_16x16x32_bf16 v[18:21], v[204:207], v[232:235], v[18:21]
	v_mfma_f32_16x16x32_bf16 v[6:9], v[196:199], v[240:243], v[6:9]
	v_mfma_f32_16x16x32_bf16 v[2:5], v[204:207], v[240:243], v[2:5]
	v_mfma_f32_16x16x32_bf16 v[54:57], v[200:203], v[216:219], v[54:57]
	v_mfma_f32_16x16x32_bf16 v[50:53], v[208:211], v[216:219], v[50:53]
	v_mfma_f32_16x16x32_bf16 v[38:41], v[200:203], v[228:231], v[38:41]
	v_mfma_f32_16x16x32_bf16 v[34:37], v[208:211], v[228:231], v[34:37]
	v_mfma_f32_16x16x32_bf16 v[22:25], v[200:203], v[236:239], v[22:25]
	v_mfma_f32_16x16x32_bf16 v[18:21], v[208:211], v[236:239], v[18:21]
	v_mfma_f32_16x16x32_bf16 v[6:9], v[200:203], v[244:247], v[6:9]
	v_mfma_f32_16x16x32_bf16 v[2:5], v[208:211], v[244:247], v[2:5]
	s_setprio 0
	s_barrier
	s_add_i32 s47, 0, 0x18000
	s_add_i32 s62, 0, 0x1c000
	v_add_u32_e32 v192, s47, v147
	v_add_u32_e32 v208, s62, v147
	ds_read_b128 v[164:167], v192
	ds_read_b128 v[184:187], v192 offset:1024
	ds_read_b128 v[188:191], v192 offset:2048
	ds_read_b128 v[192:195], v192 offset:3072
	ds_read_b128 v[196:199], v208
	ds_read_b128 v[200:203], v208 offset:1024
	ds_read_b128 v[204:207], v208 offset:2048
	ds_read_b128 v[208:211], v208 offset:3072
	s_add_u32 s6, s6, 0x40000
	s_addc_u32 s7, s7, 0
	s_mov_b32 m0, s51
	v_lshl_add_u64 v[252:253], s[6:7], 0, v[134:135]
	ds_read_b128 v[212:215], v163 offset:32768
	ds_read_b128 v[216:219], v163 offset:33792
	ds_read_b128 v[224:227], v163 offset:34816
	ds_read_b128 v[228:231], v163 offset:35840
	ds_read_b128 v[232:235], v163 offset:36864
	ds_read_b128 v[236:239], v163 offset:37888
	ds_read_b128 v[240:243], v163 offset:38912
	ds_read_b128 v[244:247], v163 offset:39936
	global_load_lds_dwordx4 v[252:253], off
	v_lshl_add_u64 v[252:253], s[6:7], 0, v[132:133]
	s_mov_b32 m0, s52
	s_nop 0
	global_load_lds_dwordx4 v[252:253], off
	s_waitcnt vmcnt(8)
	s_waitcnt lgkmcnt(0)
	s_barrier
	s_setprio 1
	s_waitcnt lgkmcnt(0)
	v_mfma_f32_16x16x32_bf16 v[126:129], v[164:167], v[212:215], v[126:129]
	v_mfma_f32_16x16x32_bf16 v[122:125], v[188:191], v[212:215], v[122:125]
	v_mfma_f32_16x16x32_bf16 v[110:113], v[164:167], v[224:227], v[110:113]
	v_mfma_f32_16x16x32_bf16 v[106:109], v[188:191], v[224:227], v[106:109]
	v_mfma_f32_16x16x32_bf16 v[94:97], v[164:167], v[232:235], v[94:97]
	v_mfma_f32_16x16x32_bf16 v[90:93], v[188:191], v[232:235], v[90:93]
	v_mfma_f32_16x16x32_bf16 v[78:81], v[164:167], v[240:243], v[78:81]
	v_mfma_f32_16x16x32_bf16 v[74:77], v[188:191], v[240:243], v[74:77]
	v_mfma_f32_16x16x32_bf16 v[126:129], v[184:187], v[216:219], v[126:129]
	v_mfma_f32_16x16x32_bf16 v[122:125], v[192:195], v[216:219], v[122:125]
	v_mfma_f32_16x16x32_bf16 v[110:113], v[184:187], v[228:231], v[110:113]
	v_mfma_f32_16x16x32_bf16 v[106:109], v[192:195], v[228:231], v[106:109]
	v_mfma_f32_16x16x32_bf16 v[94:97], v[184:187], v[236:239], v[94:97]
	v_mfma_f32_16x16x32_bf16 v[90:93], v[192:195], v[236:239], v[90:93]
	v_mfma_f32_16x16x32_bf16 v[78:81], v[184:187], v[244:247], v[78:81]
	v_mfma_f32_16x16x32_bf16 v[74:77], v[192:195], v[244:247], v[74:77]
	s_setprio 0
	s_setprio 1
	v_mfma_f32_16x16x32_bf16 v[118:121], v[196:199], v[212:215], v[118:121]
	v_mfma_f32_16x16x32_bf16 v[114:117], v[204:207], v[212:215], v[114:117]
	v_mfma_f32_16x16x32_bf16 v[102:105], v[196:199], v[224:227], v[102:105]
	v_mfma_f32_16x16x32_bf16 v[98:101], v[204:207], v[224:227], v[98:101]
	v_mfma_f32_16x16x32_bf16 v[86:89], v[196:199], v[232:235], v[86:89]
	v_mfma_f32_16x16x32_bf16 v[82:85], v[204:207], v[232:235], v[82:85]
	v_mfma_f32_16x16x32_bf16 v[70:73], v[196:199], v[240:243], v[70:73]
	v_mfma_f32_16x16x32_bf16 v[66:69], v[204:207], v[240:243], v[66:69]
	v_mfma_f32_16x16x32_bf16 v[118:121], v[200:203], v[216:219], v[118:121]
	v_mfma_f32_16x16x32_bf16 v[114:117], v[208:211], v[216:219], v[114:117]
	v_mfma_f32_16x16x32_bf16 v[102:105], v[200:203], v[228:231], v[102:105]
	v_mfma_f32_16x16x32_bf16 v[98:101], v[208:211], v[228:231], v[98:101]
	v_mfma_f32_16x16x32_bf16 v[86:89], v[200:203], v[236:239], v[86:89]
	v_mfma_f32_16x16x32_bf16 v[82:85], v[208:211], v[236:239], v[82:85]
	v_mfma_f32_16x16x32_bf16 v[70:73], v[200:203], v[244:247], v[70:73]
	v_mfma_f32_16x16x32_bf16 v[66:69], v[208:211], v[244:247], v[66:69]
	s_setprio 0
	s_barrier
	s_add_i32 s6, s47, s48
	v_lshl_add_u64 v[160:161], v[160:161], 0, s[12:13]
	s_mov_b32 m0, s6
	ds_read_b128 v[212:215], v163 offset:49152
	ds_read_b128 v[216:219], v163 offset:50176
	ds_read_b128 v[224:227], v163 offset:51200
	ds_read_b128 v[228:231], v163 offset:52224
	ds_read_b128 v[232:235], v163 offset:53248
	ds_read_b128 v[236:239], v163 offset:54272
	ds_read_b128 v[240:243], v163 offset:55296
	ds_read_b128 v[244:247], v163 offset:56320
	global_load_lds_dwordx4 v[160:161], off
	s_add_i32 m0, s6, 0x2000
	s_add_u32 s2, s2, 0x40080
	v_lshl_add_u64 v[160:161], v[168:169], 0, s[12:13]
	s_addc_u32 s3, s3, 0
	s_add_i32 s6, s62, s48
	global_load_lds_dwordx4 v[160:161], off
	v_lshl_add_u64 v[160:161], s[2:3], 0, v[0:1]
	s_mov_b32 m0, s6
	s_nop 0
	global_load_lds_dwordx4 v[160:161], off
	v_lshl_add_u64 v[160:161], s[2:3], 0, v[130:131]
	s_add_i32 m0, s6, 0x2000
	s_nop 0
	global_load_lds_dwordx4 v[160:161], off
	v_lshl_add_u64 v[160:161], v[248:249], 0, s[12:13]
	s_mov_b32 m0, s54
	s_nop 0
	global_load_lds_dwordx4 v[160:161], off
	v_lshl_add_u64 v[160:161], v[250:251], 0, s[12:13]
	s_mov_b32 m0, s55
	s_nop 0
	global_load_lds_dwordx4 v[160:161], off
	s_waitcnt vmcnt(8)
	s_waitcnt lgkmcnt(0)
	s_barrier
	s_setprio 1
	s_waitcnt lgkmcnt(0)
	v_mfma_f32_16x16x32_bf16 v[62:65], v[164:167], v[212:215], v[62:65]
	v_mfma_f32_16x16x32_bf16 v[58:61], v[188:191], v[212:215], v[58:61]
	v_mfma_f32_16x16x32_bf16 v[46:49], v[164:167], v[224:227], v[46:49]
	v_mfma_f32_16x16x32_bf16 v[42:45], v[188:191], v[224:227], v[42:45]
	v_mfma_f32_16x16x32_bf16 v[30:33], v[164:167], v[232:235], v[30:33]
	v_mfma_f32_16x16x32_bf16 v[26:29], v[188:191], v[232:235], v[26:29]
	v_mfma_f32_16x16x32_bf16 v[14:17], v[164:167], v[240:243], v[14:17]
	v_mfma_f32_16x16x32_bf16 v[10:13], v[188:191], v[240:243], v[10:13]
	v_mfma_f32_16x16x32_bf16 v[62:65], v[184:187], v[216:219], v[62:65]
	v_mfma_f32_16x16x32_bf16 v[58:61], v[192:195], v[216:219], v[58:61]
	v_mfma_f32_16x16x32_bf16 v[46:49], v[184:187], v[228:231], v[46:49]
	v_mfma_f32_16x16x32_bf16 v[42:45], v[192:195], v[228:231], v[42:45]
	v_mfma_f32_16x16x32_bf16 v[30:33], v[184:187], v[236:239], v[30:33]
	v_mfma_f32_16x16x32_bf16 v[26:29], v[192:195], v[236:239], v[26:29]
	v_mfma_f32_16x16x32_bf16 v[14:17], v[184:187], v[244:247], v[14:17]
	v_mfma_f32_16x16x32_bf16 v[10:13], v[192:195], v[244:247], v[10:13]
	s_setprio 0
	s_setprio 1
	v_mfma_f32_16x16x32_bf16 v[54:57], v[196:199], v[212:215], v[54:57]
	v_mfma_f32_16x16x32_bf16 v[50:53], v[204:207], v[212:215], v[50:53]
	v_mfma_f32_16x16x32_bf16 v[38:41], v[196:199], v[224:227], v[38:41]
	v_mfma_f32_16x16x32_bf16 v[34:37], v[204:207], v[224:227], v[34:37]
	v_mfma_f32_16x16x32_bf16 v[22:25], v[196:199], v[232:235], v[22:25]
	v_mfma_f32_16x16x32_bf16 v[18:21], v[204:207], v[232:235], v[18:21]
	v_mfma_f32_16x16x32_bf16 v[6:9], v[196:199], v[240:243], v[6:9]
	v_mfma_f32_16x16x32_bf16 v[2:5], v[204:207], v[240:243], v[2:5]
	v_mfma_f32_16x16x32_bf16 v[54:57], v[200:203], v[216:219], v[54:57]
	v_mfma_f32_16x16x32_bf16 v[50:53], v[208:211], v[216:219], v[50:53]
	v_mfma_f32_16x16x32_bf16 v[38:41], v[200:203], v[228:231], v[38:41]
	v_mfma_f32_16x16x32_bf16 v[34:37], v[208:211], v[228:231], v[34:37]
	v_mfma_f32_16x16x32_bf16 v[22:25], v[200:203], v[236:239], v[22:25]
	v_mfma_f32_16x16x32_bf16 v[18:21], v[208:211], v[236:239], v[18:21]
	v_mfma_f32_16x16x32_bf16 v[6:9], v[200:203], v[244:247], v[6:9]
	v_mfma_f32_16x16x32_bf16 v[2:5], v[208:211], v[244:247], v[2:5]
	s_setprio 0
	s_barrier
	s_add_i32 s46, s46, 2
	s_add_u32 s60, s60, 0x100
	s_addc_u32 s61, s61, 0
	s_add_u32 s40, s40, 0x100
	s_addc_u32 s41, s41, 0
	s_cmp_gt_u32 s46, 13
	s_cbranch_scc0 .LBB0_561
	s_and_b64 vcc, exec, s[30:31]
	s_cbranch_vccz .LBB0_564
	s_barrier
